# GEMM tile loops: 128 accumulator zeroing v_mov_b32 replaced by 64 v_mov_b64 (four tile-loop headers)
# speedup vs baseline: 1.0035x; 1.0035x over previous
.LBB0_172:
	v_mov_b64_e32 v[0:1], 0x1080
	s_ashr_i32 s57, s56, 31
	v_cmp_lt_i64_e32 vcc, s[58:59], v[0:1]
	s_lshl_b64 s[58:59], s[56:57], 20
	v_readlane_b32 s34, v255, 26
	v_readlane_b32 s35, v255, 27
	s_add_u32 s58, s34, s58
	s_addc_u32 s59, s35, s59
	s_and_b64 s[60:61], vcc, exec
	s_cselect_b32 s57, s59, s63
	s_cselect_b32 s71, s58, s62
	s_ashr_i32 s55, s54, 31
	s_lshl_b64 s[60:61], s[54:55], 20
	s_add_u32 s60, s33, s60
	s_addc_u32 s61, s37, s61
	s_and_b64 s[66:67], vcc, exec
	s_cselect_b32 s55, s61, s65
	s_cselect_b32 s80, s60, s64
	s_add_u32 s81, s64, 0x100
	v_mov_b64_e32 v[0:1], 0
	v_mov_b64_e32 v[2:3], 0
	v_mov_b64_e32 v[4:5], 0
	v_mov_b64_e32 v[6:7], 0
	v_mov_b64_e32 v[8:9], 0
	v_mov_b64_e32 v[10:11], 0
	v_mov_b64_e32 v[12:13], 0
	v_mov_b64_e32 v[14:15], 0
	v_mov_b64_e32 v[16:17], 0
	v_mov_b64_e32 v[18:19], 0
	v_mov_b64_e32 v[20:21], 0
	v_mov_b64_e32 v[22:23], 0
	v_mov_b64_e32 v[24:25], 0
	v_mov_b64_e32 v[26:27], 0
	v_mov_b64_e32 v[28:29], 0
	v_mov_b64_e32 v[30:31], 0
	v_mov_b64_e32 v[32:33], 0
	v_mov_b64_e32 v[34:35], 0
	v_mov_b64_e32 v[36:37], 0
	v_mov_b64_e32 v[38:39], 0
	v_mov_b64_e32 v[40:41], 0
	v_mov_b64_e32 v[42:43], 0
	v_mov_b64_e32 v[44:45], 0
	v_mov_b64_e32 v[46:47], 0
	v_mov_b64_e32 v[48:49], 0
	v_mov_b64_e32 v[50:51], 0
	v_mov_b64_e32 v[52:53], 0
	v_mov_b64_e32 v[54:55], 0
	v_mov_b64_e32 v[56:57], 0
	v_mov_b64_e32 v[58:59], 0
	v_mov_b64_e32 v[60:61], 0
	v_mov_b64_e32 v[62:63], 0
	v_mov_b64_e32 v[64:65], 0
	v_mov_b64_e32 v[66:67], 0
	v_mov_b64_e32 v[68:69], 0
	v_mov_b64_e32 v[70:71], 0
	v_mov_b64_e32 v[72:73], 0
	v_mov_b64_e32 v[74:75], 0
	v_mov_b64_e32 v[76:77], 0
	v_mov_b64_e32 v[78:79], 0
	v_mov_b64_e32 v[80:81], 0
	v_mov_b64_e32 v[82:83], 0
	v_mov_b64_e32 v[84:85], 0
	v_mov_b64_e32 v[86:87], 0
	v_mov_b64_e32 v[88:89], 0
	v_mov_b64_e32 v[90:91], 0
	v_mov_b64_e32 v[92:93], 0
	v_mov_b64_e32 v[94:95], 0
	v_mov_b64_e32 v[110:111], 0
	v_mov_b64_e32 v[112:113], 0
	v_mov_b64_e32 v[114:115], 0
	v_mov_b64_e32 v[116:117], 0
	v_mov_b64_e32 v[118:119], 0
	v_mov_b64_e32 v[120:121], 0
	v_mov_b64_e32 v[122:123], 0
	v_mov_b64_e32 v[124:125], 0
	v_mov_b64_e32 v[126:127], 0
	v_mov_b64_e32 v[128:129], 0
	v_mov_b64_e32 v[130:131], 0
	v_mov_b64_e32 v[132:133], 0
	v_mov_b64_e32 v[134:135], 0
	v_mov_b64_e32 v[136:137], 0
	v_mov_b64_e32 v[138:139], 0
	v_mov_b64_e32 v[140:141], 0
	s_addc_u32 s82, s65, 0
	s_mov_b32 s83, -2

.LBB0_263:
	s_add_u32 s59, s24, 0x100
	s_addc_u32 s60, s25, 0
	s_add_u32 s8, s26, 0x80
	v_mov_b64_e32 v[0:1], 0
	v_mov_b64_e32 v[2:3], 0
	v_mov_b64_e32 v[4:5], 0
	v_mov_b64_e32 v[6:7], 0
	v_mov_b64_e32 v[8:9], 0
	v_mov_b64_e32 v[10:11], 0
	v_mov_b64_e32 v[12:13], 0
	v_mov_b64_e32 v[14:15], 0
	v_mov_b64_e32 v[16:17], 0
	v_mov_b64_e32 v[18:19], 0
	v_mov_b64_e32 v[20:21], 0
	v_mov_b64_e32 v[22:23], 0
	v_mov_b64_e32 v[24:25], 0
	v_mov_b64_e32 v[26:27], 0
	v_mov_b64_e32 v[28:29], 0
	v_mov_b64_e32 v[30:31], 0
	v_mov_b64_e32 v[32:33], 0
	v_mov_b64_e32 v[34:35], 0
	v_mov_b64_e32 v[36:37], 0
	v_mov_b64_e32 v[38:39], 0
	v_mov_b64_e32 v[40:41], 0
	v_mov_b64_e32 v[42:43], 0
	v_mov_b64_e32 v[44:45], 0
	v_mov_b64_e32 v[46:47], 0
	v_mov_b64_e32 v[48:49], 0
	v_mov_b64_e32 v[50:51], 0
	v_mov_b64_e32 v[52:53], 0
	v_mov_b64_e32 v[54:55], 0
	v_mov_b64_e32 v[56:57], 0
	v_mov_b64_e32 v[58:59], 0
	v_mov_b64_e32 v[60:61], 0
	v_mov_b64_e32 v[62:63], 0
	v_mov_b64_e32 v[64:65], 0
	v_mov_b64_e32 v[66:67], 0
	v_mov_b64_e32 v[68:69], 0
	v_mov_b64_e32 v[70:71], 0
	v_mov_b64_e32 v[72:73], 0
	v_mov_b64_e32 v[74:75], 0
	v_mov_b64_e32 v[76:77], 0
	v_mov_b64_e32 v[78:79], 0
	v_mov_b64_e32 v[80:81], 0
	v_mov_b64_e32 v[82:83], 0
	v_mov_b64_e32 v[84:85], 0
	v_mov_b64_e32 v[86:87], 0
	v_mov_b64_e32 v[88:89], 0
	v_mov_b64_e32 v[90:91], 0
	v_mov_b64_e32 v[92:93], 0
	v_mov_b64_e32 v[94:95], 0
	v_mov_b64_e32 v[96:97], 0
	v_mov_b64_e32 v[98:99], 0
	v_mov_b64_e32 v[100:101], 0
	v_mov_b64_e32 v[102:103], 0
	v_mov_b64_e32 v[104:105], 0
	v_mov_b64_e32 v[106:107], 0
	v_mov_b64_e32 v[108:109], 0
	v_mov_b64_e32 v[110:111], 0
	v_mov_b64_e32 v[112:113], 0
	v_mov_b64_e32 v[114:115], 0
	v_mov_b64_e32 v[116:117], 0
	v_mov_b64_e32 v[118:119], 0
	v_mov_b64_e32 v[120:121], 0
	v_mov_b64_e32 v[122:123], 0
	v_mov_b64_e32 v[124:125], 0
	v_mov_b64_e32 v[126:127], 0
	s_addc_u32 s9, s27, 0
	s_mov_b32 s24, 0

.LBB0_638:
	v_mov_b64_e32 v[0:1], s[4:5]
	s_ashr_i32 s15, s14, 31
	v_cmp_lt_i64_e32 vcc, s[20:21], v[0:1]
	s_lshl_b64 s[20:21], s[14:15], s50
	s_add_u32 s13, s37, s20
	s_addc_u32 s15, s38, s21
	s_and_b64 s[20:21], vcc, exec
	s_cselect_b32 s21, s15, s27
	s_cselect_b32 s20, s13, s26
	s_ashr_i32 s13, s12, 31
	s_lshl_b64 s[24:25], s[12:13], s50
	s_add_u32 s13, s39, s24
	s_addc_u32 s15, s46, s25
	s_and_b64 s[24:25], vcc, exec
	s_cselect_b32 s25, s15, s31
	s_cselect_b32 s24, s13, s30
	s_add_u32 s26, s26, 0x80
	s_addc_u32 s27, s27, 0
	s_add_u32 s13, s30, 0x100
	v_mov_b64_e32 v[0:1], 0
	v_mov_b64_e32 v[2:3], 0
	v_mov_b64_e32 v[4:5], 0
	v_mov_b64_e32 v[6:7], 0
	v_mov_b64_e32 v[8:9], 0
	v_mov_b64_e32 v[10:11], 0
	v_mov_b64_e32 v[12:13], 0
	v_mov_b64_e32 v[14:15], 0
	v_mov_b64_e32 v[16:17], 0
	v_mov_b64_e32 v[18:19], 0
	v_mov_b64_e32 v[20:21], 0
	v_mov_b64_e32 v[22:23], 0
	v_mov_b64_e32 v[24:25], 0
	v_mov_b64_e32 v[26:27], 0
	v_mov_b64_e32 v[28:29], 0
	v_mov_b64_e32 v[30:31], 0
	v_mov_b64_e32 v[32:33], 0
	v_mov_b64_e32 v[34:35], 0
	v_mov_b64_e32 v[36:37], 0
	v_mov_b64_e32 v[38:39], 0
	v_mov_b64_e32 v[40:41], 0
	v_mov_b64_e32 v[42:43], 0
	v_mov_b64_e32 v[44:45], 0
	v_mov_b64_e32 v[46:47], 0
	v_mov_b64_e32 v[48:49], 0
	v_mov_b64_e32 v[50:51], 0
	v_mov_b64_e32 v[52:53], 0
	v_mov_b64_e32 v[54:55], 0
	v_mov_b64_e32 v[56:57], 0
	v_mov_b64_e32 v[58:59], 0
	v_mov_b64_e32 v[60:61], 0
	v_mov_b64_e32 v[62:63], 0
	v_mov_b64_e32 v[64:65], 0
	v_mov_b64_e32 v[66:67], 0
	v_mov_b64_e32 v[68:69], 0
	v_mov_b64_e32 v[70:71], 0
	v_mov_b64_e32 v[72:73], 0
	v_mov_b64_e32 v[74:75], 0
	v_mov_b64_e32 v[76:77], 0
	v_mov_b64_e32 v[78:79], 0
	v_mov_b64_e32 v[80:81], 0
	v_mov_b64_e32 v[82:83], 0
	v_mov_b64_e32 v[84:85], 0
	v_mov_b64_e32 v[86:87], 0
	v_mov_b64_e32 v[88:89], 0
	v_mov_b64_e32 v[90:91], 0
	v_mov_b64_e32 v[92:93], 0
	v_mov_b64_e32 v[94:95], 0
	v_mov_b64_e32 v[96:97], 0
	v_mov_b64_e32 v[98:99], 0
	v_mov_b64_e32 v[100:101], 0
	v_mov_b64_e32 v[102:103], 0
	v_mov_b64_e32 v[104:105], 0
	v_mov_b64_e32 v[106:107], 0
	v_mov_b64_e32 v[108:109], 0
	v_mov_b64_e32 v[110:111], 0
	v_mov_b64_e32 v[112:113], 0
	v_mov_b64_e32 v[114:115], 0
	v_mov_b64_e32 v[116:117], 0
	v_mov_b64_e32 v[118:119], 0
	v_mov_b64_e32 v[120:121], 0
	v_mov_b64_e32 v[122:123], 0
	v_mov_b64_e32 v[124:125], 0
	v_mov_b64_e32 v[126:127], 0
	s_addc_u32 s15, s31, 0
	s_mov_b32 s30, 0

.LBB0_655:
	v_mov_b64_e32 v[0:1], s[2:3]
	s_ashr_i32 s9, s8, 31
	v_cmp_lt_i64_e32 vcc, s[10:11], v[0:1]
	s_lshl_b64 s[10:11], s[8:9], 20
	v_readlane_b32 s12, v255, 26
	v_readlane_b32 s13, v255, 27
	s_add_u32 s10, s12, s10
	s_addc_u32 s11, s13, s11
	s_and_b64 s[12:13], vcc, exec
	s_cselect_b32 s9, s11, s21
	s_cselect_b32 s15, s10, s20
	s_ashr_i32 s5, s4, 31
	s_lshl_b64 s[12:13], s[4:5], 20
	s_add_u32 s12, s26, s12
	s_addc_u32 s13, s27, s13
	s_and_b64 s[24:25], vcc, exec
	s_cselect_b32 s5, s13, s19
	s_cselect_b32 s17, s12, s18
	s_add_u32 s44, s18, 0x100
	s_addc_u32 s53, s19, 0
	s_add_u32 s18, s20, 0x80080
	v_mov_b64_e32 v[0:1], 0
	v_mov_b64_e32 v[2:3], 0
	v_mov_b64_e32 v[4:5], 0
	v_mov_b64_e32 v[6:7], 0
	v_mov_b64_e32 v[8:9], 0
	v_mov_b64_e32 v[10:11], 0
	v_mov_b64_e32 v[12:13], 0
	v_mov_b64_e32 v[14:15], 0
	v_mov_b64_e32 v[16:17], 0
	v_mov_b64_e32 v[18:19], 0
	v_mov_b64_e32 v[20:21], 0
	v_mov_b64_e32 v[22:23], 0
	v_mov_b64_e32 v[24:25], 0
	v_mov_b64_e32 v[26:27], 0
	v_mov_b64_e32 v[28:29], 0
	v_mov_b64_e32 v[30:31], 0
	v_mov_b64_e32 v[32:33], 0
	v_mov_b64_e32 v[34:35], 0
	v_mov_b64_e32 v[36:37], 0
	v_mov_b64_e32 v[38:39], 0
	v_mov_b64_e32 v[40:41], 0
	v_mov_b64_e32 v[42:43], 0
	v_mov_b64_e32 v[44:45], 0
	v_mov_b64_e32 v[46:47], 0
	v_mov_b64_e32 v[48:49], 0
	v_mov_b64_e32 v[50:51], 0
	v_mov_b64_e32 v[52:53], 0
	v_mov_b64_e32 v[54:55], 0
	v_mov_b64_e32 v[56:57], 0
	v_mov_b64_e32 v[58:59], 0
	v_mov_b64_e32 v[60:61], 0
	v_mov_b64_e32 v[62:63], 0
	v_mov_b64_e32 v[64:65], 0
	v_mov_b64_e32 v[66:67], 0
	v_mov_b64_e32 v[68:69], 0
	v_mov_b64_e32 v[70:71], 0
	v_mov_b64_e32 v[72:73], 0
	v_mov_b64_e32 v[74:75], 0
	v_mov_b64_e32 v[76:77], 0
	v_mov_b64_e32 v[78:79], 0
	v_mov_b64_e32 v[80:81], 0
	v_mov_b64_e32 v[82:83], 0
	v_mov_b64_e32 v[84:85], 0
	v_mov_b64_e32 v[86:87], 0
	v_mov_b64_e32 v[88:89], 0
	v_mov_b64_e32 v[90:91], 0
	v_mov_b64_e32 v[92:93], 0
	v_mov_b64_e32 v[94:95], 0
	v_mov_b64_e32 v[96:97], 0
	v_mov_b64_e32 v[98:99], 0
	v_mov_b64_e32 v[100:101], 0
	v_mov_b64_e32 v[102:103], 0
	v_mov_b64_e32 v[104:105], 0
	v_mov_b64_e32 v[106:107], 0
	v_mov_b64_e32 v[108:109], 0
	v_mov_b64_e32 v[110:111], 0
	v_mov_b64_e32 v[112:113], 0
	v_mov_b64_e32 v[114:115], 0
	v_mov_b64_e32 v[116:117], 0
	v_mov_b64_e32 v[118:119], 0
	v_mov_b64_e32 v[120:121], 0
	v_mov_b64_e32 v[122:123], 0
	v_mov_b64_e32 v[124:125], 0
	v_mov_b64_e32 v[126:127], 0
	s_addc_u32 s19, s21, 0
	s_mov_b32 s54, -2
